# strategy 9 loop-edge edits: both attention tile loops compute the next iteration's scalar head and issue its prefetch loads before the loop-back barrier, then branch straight into the compute segment
# speedup vs baseline: 1.0090x; 1.0077x over previous
.Lwh500:
	s_add_i32 s7, s7, 64
	s_add_i32 s0, s21, s22
	s_cmp_lg_u32 s0, 4
	v_subrev_u32_e32 v197, 64, v197
	v_mov_b32_e32 v198, v199
	s_waitcnt lgkmcnt(0)
	s_cbranch_scc0 .Lwh_exitb
	s_mov_b64 s[2:3], s[14:15]
	s_mov_b32 s8, s22
	s_add_i32 s0, s8, 2
	s_cmp_lt_i32 s0, s18
	s_cselect_b64 s[12:13], -1, 0
	s_cmp_ge_i32 s0, s18
	s_cbranch_scc1 .Lwh491
	s_add_i32 s1, s6, s8
	s_add_i32 s4, s21, s8
	s_add_i32 s1, s1, 2
	s_add_i32 s4, s4, 34
	s_cmp_lt_i32 s0, s27
	s_cselect_b32 s0, s1, s4
	v_lshl_add_u32 v14, s0, 6, v194
	v_ashrrev_i32_e32 v15, 31, v14
	v_lshlrev_b64 v[14:15], 9, v[14:15]
	v_lshl_add_u64 v[14:15], v[190:191], 0, v[14:15]
	global_load_dwordx4 v[184:187], v[14:15], off

.Lwh493:
	s_andn2_b64 s[0:1], exec, s[4:5]
	s_andn2_b64 vcc, exec, s[4:5]
	s_mov_b64 s[14:15], 0
	s_cbranch_vccnz .Lwh495
	s_cmp_ge_i32 s22, s27
	s_cselect_b64 s[4:5], -1, 0
	s_add_i32 s9, s7, 63
	s_cmp_ge_i32 s9, s16
	s_cselect_b64 s[14:15], -1, 0
	s_cmp_le_i32 s7, s17
	s_cselect_b64 s[28:29], -1, 0
	s_and_b64 s[14:15], s[14:15], s[28:29]
	s_or_b64 s[14:15], s[4:5], s[14:15]
.Lwh495:
	s_bitcmp1_b32 s22, 0
	s_cselect_b32 s23, 0x2400, 0
	s_add_i32 s30, s23, 0
	s_bitcmp1_b32 s8, 0
	s_cselect_b32 s28, 0x2400, 0
	s_and_b64 s[4:5], s[2:3], s[14:15]
	s_add_i32 s29, s28, 0
	s_andn2_b64 vcc, exec, s[4:5]
	s_mov_b64 s[4:5], -1
	s_barrier
	s_cbranch_vccnz .LBB0_502
	s_branch .LBB0_513
.Lwh_exitb:
	s_barrier

.LBB0_543:
	v_add_f32_e32 v39, v129, v130
	v_add_f32_e32 v39, v110, v39
	v_add_f32_e32 v41, v147, v148
	v_exp_f32_e32 v37, v47
	v_exp_f32_e32 v35, v63
	v_exp_f32_e32 v40, v52
	v_exp_f32_e32 v38, v64
	v_exp_f32_e32 v34, v66
	v_exp_f32_e32 v124, v67
	v_exp_f32_e32 v36, v68
	v_exp_f32_e32 v125, v69
	v_exp_f32_e32 v129, v55
	v_exp_f32_e32 v130, v57
	v_add_f32_e32 v110, v39, v41
	v_exp_f32_e32 v39, v70
	v_exp_f32_e32 v41, v71
	v_exp_f32_e32 v122, v76
	v_exp_f32_e32 v123, v77
	s_andn2_b64 vcc, exec, s[20:21]
	s_waitcnt vmcnt(0)
	ds_write_b128 v111, v[106:109] offset:18432
	s_waitcnt lgkmcnt(0)
	s_cbranch_vccz .Ldr_exit
	s_mov_b32 s25, s26
	s_add_i32 s27, s25, 3
	s_add_i32 s28, s24, s25
	s_cmp_lt_u32 s27, s7
	s_cselect_b64 s[2:3], -1, 0
	s_cbranch_scc0 .Ldr_nol
	s_add_i32 s4, s28, 35
	s_cmp_lt_u32 s27, s23
	s_cselect_b32 s4, s27, s4
	v_lshl_add_u32 v48, s4, 6, v117
	v_ashrrev_i32_e32 v49, 31, v48
	v_lshlrev_b64 v[48:49], 8, v[48:49]
	v_lshl_add_u64 v[48:49], v[112:113], 0, v[48:49]
	global_load_dwordx4 v[98:101], v[48:49], off
.Ldr_nol:
	s_barrier
	s_branch .LBB0_537
